# zero the accumulators with 64 v_mov_b64 per unit instead of 128 v_mov_b32
# speedup vs baseline: 1.0108x; 1.0031x over previous
; template <class Epi, class Sched, bool ALIGN_EPI = false, bool SP2 = false>
; __device__ __forceinline__ void gemm_phase(PG8_LAS unsigned char* lds, const Gemm g, const Sched& S, const Epi& E) {
;     ...
;         if (epi_now) {
; #pragma unroll
;         for (int a = 0; a < 2; ++a)
; #pragma unroll
;             for (int b = 0; b < 2; ++b)
; #pragma unroll
;                 for (int m = 0; m < 4; ++m)
; #pragma unroll
;                     for (int n = 0; n < 2; ++n) acc[a][b][m][n] = (f32x4){0.f, 0.f, 0.f, 0.f};
;         }
;         cur = nxt; cA = nA; cB = nB; ++ui;
.LBB0_62:
	s_add_u32 s44, s66, 0x80
	s_addc_u32 s45, s67, 0
	s_add_u32 s19, s46, 0x100
	v_mov_b32_e32 v0, 0
	s_addc_u32 s20, s47, 0
	s_mov_b32 s46, 0
	v_mov_b64_e32 v[0:1], 0
	v_mov_b64_e32 v[2:3], 0
	v_mov_b64_e32 v[4:5], 0
	v_mov_b64_e32 v[6:7], 0
	v_mov_b64_e32 v[16:17], 0
	v_mov_b64_e32 v[18:19], 0
	v_mov_b64_e32 v[20:21], 0
	v_mov_b64_e32 v[22:23], 0
	v_mov_b64_e32 v[32:33], 0
	v_mov_b64_e32 v[34:35], 0
	v_mov_b64_e32 v[36:37], 0
	v_mov_b64_e32 v[38:39], 0
	v_mov_b64_e32 v[48:49], 0
	v_mov_b64_e32 v[50:51], 0
	v_mov_b64_e32 v[52:53], 0
	v_mov_b64_e32 v[54:55], 0
	v_mov_b64_e32 v[8:9], 0
	v_mov_b64_e32 v[10:11], 0
	v_mov_b64_e32 v[12:13], 0
	v_mov_b64_e32 v[14:15], 0
	v_mov_b64_e32 v[24:25], 0
	v_mov_b64_e32 v[26:27], 0
	v_mov_b64_e32 v[28:29], 0
	v_mov_b64_e32 v[30:31], 0
	v_mov_b64_e32 v[40:41], 0
	v_mov_b64_e32 v[42:43], 0
	v_mov_b64_e32 v[44:45], 0
	v_mov_b64_e32 v[46:47], 0
	v_mov_b64_e32 v[56:57], 0
	v_mov_b64_e32 v[58:59], 0
	v_mov_b64_e32 v[60:61], 0
	v_mov_b64_e32 v[62:63], 0
	v_mov_b64_e32 v[64:65], 0
	v_mov_b64_e32 v[66:67], 0
	v_mov_b64_e32 v[68:69], 0
	v_mov_b64_e32 v[70:71], 0
	v_mov_b64_e32 v[80:81], 0
	v_mov_b64_e32 v[82:83], 0
	v_mov_b64_e32 v[84:85], 0
	v_mov_b64_e32 v[86:87], 0
	v_mov_b64_e32 v[96:97], 0
	v_mov_b64_e32 v[98:99], 0
	v_mov_b64_e32 v[100:101], 0
	v_mov_b64_e32 v[102:103], 0
	v_mov_b64_e32 v[112:113], 0
	v_mov_b64_e32 v[114:115], 0
	v_mov_b64_e32 v[116:117], 0
	v_mov_b64_e32 v[118:119], 0
	v_mov_b64_e32 v[72:73], 0
	v_mov_b64_e32 v[74:75], 0
	v_mov_b64_e32 v[76:77], 0
	v_mov_b64_e32 v[78:79], 0
	v_mov_b64_e32 v[88:89], 0
	v_mov_b64_e32 v[90:91], 0
	v_mov_b64_e32 v[92:93], 0
	v_mov_b64_e32 v[94:95], 0
	v_mov_b64_e32 v[104:105], 0
	v_mov_b64_e32 v[106:107], 0
	v_mov_b64_e32 v[108:109], 0
	v_mov_b64_e32 v[110:111], 0
	v_mov_b64_e32 v[120:121], 0
	v_mov_b64_e32 v[122:123], 0
	v_mov_b64_e32 v[124:125], 0
	v_mov_b64_e32 v[126:127], 0

;     __device__ __forceinline__ const char* aptr(const Unit& u, const Gemm& g) const { return (const char*)g.A + (long)(u.pm >> 4) * g.adj; }
;     __device__ __forceinline__ const char* bptr(const Unit&, const Gemm& g) const { return (const char*)g.Bt; }
;     __device__ __forceinline__ bool next(int i, Unit& u) const { const int r = i / 9, tile = t0 + r * ts; if (r >= nr || tile >= 512) return false; u.pm = tile >> 2; u.pn = tile & 3; u.kind = i % 9; return true; }
; template <class Epi, class Sched, bool ALIGN_EPI = false, bool SP2 = false>
; __device__ __forceinline__ void gemm_phase(PG8_LAS unsigned char* lds, const Gemm g, const Sched& S, const Epi& E) {
;     ...
;         const bool has_next = S.next(ui + 1, nxt);
;         const char* nA = has_next ? S.aptr(nxt, g) + (size_t)nxt.pm * tstep : cA; const char* nB = has_next ? S.bptr(nxt, g) + (size_t)nxt.pn * tstep : cB;
;     ...
;         if (epi_now) {
; #pragma unroll
;         for (int a = 0; a < 2; ++a)
; #pragma unroll
;             for (int b = 0; b < 2; ++b)
; #pragma unroll
;                 for (int m = 0; m < 4; ++m)
; #pragma unroll
;                     for (int n = 0; n < 2; ++n) acc[a][b][m][n] = (f32x4){0.f, 0.f, 0.f, 0.f};
;         }
;         cur = nxt; cA = nA; cB = nB; ++ui;
.LBB0_199:
	s_ashr_i32 s51, s50, 31
	s_lshl_b64 s[18:19], s[50:51], 19
	s_add_u32 s52, s23, s18
	s_addc_u32 s53, s62, s19
	s_and_b64 s[18:19], s[40:41], exec
	s_cselect_b32 s18, s53, s57
	s_cselect_b32 s19, s52, s56
	s_ashr_i32 s49, s48, 31
	s_lshl_b64 s[54:55], s[48:49], 19
	s_add_u32 s54, s14, s54
	s_addc_u32 s55, s22, s55
	s_and_b64 s[60:61], s[40:41], exec
	s_cselect_b32 s20, s55, s59
	s_cselect_b32 s43, s54, s58
	s_add_u32 s56, s56, 0x40080
	s_addc_u32 s57, s57, 0
	s_add_u32 s49, s58, 0x100
	v_mov_b32_e32 v0, 0
	s_addc_u32 s51, s59, 0
	s_mov_b32 s76, -2
	v_mov_b64_e32 v[0:1], 0
	v_mov_b64_e32 v[2:3], 0
	v_mov_b64_e32 v[4:5], 0
	v_mov_b64_e32 v[6:7], 0
	v_mov_b64_e32 v[12:13], 0
	v_mov_b64_e32 v[14:15], 0
	v_mov_b64_e32 v[20:21], 0
	v_mov_b64_e32 v[22:23], 0
	v_mov_b64_e32 v[28:29], 0
	v_mov_b64_e32 v[30:31], 0
	v_mov_b64_e32 v[36:37], 0
	v_mov_b64_e32 v[38:39], 0
	v_mov_b64_e32 v[44:45], 0
	v_mov_b64_e32 v[46:47], 0
	v_mov_b64_e32 v[52:53], 0
	v_mov_b64_e32 v[54:55], 0
	v_mov_b64_e32 v[8:9], 0
	v_mov_b64_e32 v[10:11], 0
	v_mov_b64_e32 v[16:17], 0
	v_mov_b64_e32 v[18:19], 0
	v_mov_b64_e32 v[24:25], 0
	v_mov_b64_e32 v[26:27], 0
	v_mov_b64_e32 v[32:33], 0
	v_mov_b64_e32 v[34:35], 0
	v_mov_b64_e32 v[40:41], 0
	v_mov_b64_e32 v[42:43], 0
	v_mov_b64_e32 v[48:49], 0
	v_mov_b64_e32 v[50:51], 0
	v_mov_b64_e32 v[56:57], 0
	v_mov_b64_e32 v[58:59], 0
	v_mov_b64_e32 v[60:61], 0
	v_mov_b64_e32 v[62:63], 0
	v_mov_b64_e32 v[64:65], 0
	v_mov_b64_e32 v[66:67], 0
	v_mov_b64_e32 v[68:69], 0
	v_mov_b64_e32 v[70:71], 0
	v_mov_b64_e32 v[76:77], 0
	v_mov_b64_e32 v[78:79], 0
	v_mov_b64_e32 v[84:85], 0
	v_mov_b64_e32 v[86:87], 0
	v_mov_b64_e32 v[92:93], 0
	v_mov_b64_e32 v[94:95], 0
	v_mov_b64_e32 v[100:101], 0
	v_mov_b64_e32 v[102:103], 0
	v_mov_b64_e32 v[108:109], 0
	v_mov_b64_e32 v[110:111], 0
	v_mov_b64_e32 v[116:117], 0
	v_mov_b64_e32 v[118:119], 0
	v_mov_b64_e32 v[72:73], 0
	v_mov_b64_e32 v[74:75], 0
	v_mov_b64_e32 v[80:81], 0
	v_mov_b64_e32 v[82:83], 0
	v_mov_b64_e32 v[88:89], 0
	v_mov_b64_e32 v[90:91], 0
	v_mov_b64_e32 v[96:97], 0
	v_mov_b64_e32 v[98:99], 0
	v_mov_b64_e32 v[104:105], 0
	v_mov_b64_e32 v[106:107], 0
	v_mov_b64_e32 v[112:113], 0
	v_mov_b64_e32 v[114:115], 0
	v_mov_b64_e32 v[120:121], 0
	v_mov_b64_e32 v[122:123], 0
	v_mov_b64_e32 v[124:125], 0
	v_mov_b64_e32 v[126:127], 0

;     __device__ __forceinline__ const char* aptr(const Unit& u, const Gemm& g) const { return (const char*)g.A + (long)(u.pm >> 4) * g.adj; }
;     __device__ __forceinline__ const char* bptr(const Unit&, const Gemm& g) const { return (const char*)g.Bt; }
; #define PG8_STAGE(bufoff, gbase, voff) do { _Pragma("unroll") for (int _i = 0; _i < 2; ++_i) \
;         __builtin_amdgcn_global_load_lds((const unsigned*)((const char*)(gbase) + (voff)[_i]), (PG8_LAS unsigned*)(lds + (bufoff) + ldsw + _i * 8192), 16, 0, 0); } while (0)
; #define PG8_WAIT_V(n) asm volatile("s_waitcnt vmcnt(" #n ")" ::: "memory")
; #define PG8_BAR __builtin_amdgcn_s_barrier()
; template <class Epi, class Sched, bool ALIGN_EPI = false, bool SP2 = false>
; __device__ __forceinline__ void gemm_phase(PG8_LAS unsigned char* lds, const Gemm g, const Sched& S, const Epi& E) {
;     ...
;     f32x4 acc[2][2][4][2];
; #pragma unroll
;     for (int a = 0; a < 2; ++a)
; #pragma unroll
;         for (int b = 0; b < 2; ++b)
; #pragma unroll
;             for (int m = 0; m < 4; ++m)
; #pragma unroll
;                 for (int n = 0; n < 2; ++n) acc[a][b][m][n] = (f32x4){0.f, 0.f, 0.f, 0.f};
;     bf16x8 At[4][2], B0[2][2], B1[2][2];
;     const char* cA = S.aptr(cur, g) + (size_t)cur.pm * tstep; const char* cB = S.bptr(cur, g) + (size_t)cur.pn * tstep;
;     S.a_ready(cur);
;     if constexpr (SP2) {
;         PG8_STAGE(PG8_SB(0, 0), cB, voffB); PG8_STAGE(PG8_SB(0, 1), cB + hstep, voffB); PG8_STAGE(PG8_SA(0, 0), cA, voffA); PG8_STAGE(PG8_SA(0, 1), cA + hstep, voffA);
;         if (wr == 1) PG8_BAR;
;         PG8_WAIT_V(2); PG8_BAR;
;         PG8_STAGE(PG8_SB(1, 0), cB + kstep, voffB); PG8_STAGE(PG8_SA(1, 0), cA + kstep, voffA); PG8_STAGE(PG8_SB(1, 1), cB + hstep + kstep, voffB);
;         PG8_WAIT_V(6); PG8_BAR;
;     } else {
;         PG8_STAGE(PG8_SB(0, 0), cB, voffB); PG8_STAGE(PG8_SA(0, 0), cA, voffA); PG8_STAGE(PG8_SB(0, 1), cB + hstep, voffB); PG8_STAGE(PG8_SA(0, 1), cA + hstep, voffA);
;         if (wr == 1) PG8_BAR;
;         PG8_WAIT_V(4); PG8_BAR;
;         PG8_STAGE(PG8_SB(1, 0), cB + kstep, voffB); PG8_STAGE(PG8_SA(1, 0), cA + kstep, voffA); PG8_STAGE(PG8_SB(1, 1), cB + hstep + kstep, voffB);
;         PG8_WAIT_V(6); PG8_BAR;
.LBB0_468:
	s_and_b64 s[10:11], s[24:25], exec
	s_cselect_b32 s61, 0x200, 2
	s_cselect_b32 s62, s86, 32
	s_add_u32 s43, s90, s28
	s_mul_i32 s10, s87, 0xc00
	s_addc_u32 s49, s91, s29
	s_ashr_i32 s11, s10, 31
	s_lshl_b64 s[10:11], s[10:11], 2
	s_waitcnt lgkmcnt(0)
	s_add_u32 s63, s30, s10
	s_addc_u32 s64, s31, s11
	s_add_u32 s10, s90, s26
	s_addc_u32 s11, s91, s27
	s_lshl_b32 s26, s97, 5
	s_and_b32 s26, s26, 0xe0
	s_add_i32 s26, s26, s46
	v_bfe_u32 v16, v13, 4, 2
	s_and_b64 s[24:25], s[24:25], exec
	v_and_b32_e32 v15, 15, v13
	v_lshlrev_b32_e32 v192, 4, v16
	v_lshlrev_b32_e32 v13, 2, v13
	s_cselect_b32 s30, s80, s26
	s_and_b32 s26, s48, 3
	v_lshlrev_b32_e32 v17, 3, v16
	v_lshl_or_b32 v16, v15, 6, v192
	s_lshl_b32 s24, s47, 13
	v_and_b32_e32 v13, 32, v13
	s_add_i32 m0, s55, 0x18000
	v_lshl_add_u64 v[6:7], v[6:7], 0, s[36:37]
	v_bitop3_b32 v18, v16, s24, v13 bitop3:0xde
	s_lshl_b32 s24, s26, 12
	s_waitcnt vmcnt(2)
	s_barrier
	global_load_lds_dwordx4 v[6:7], off
	v_lshl_add_u64 v[4:5], v[4:5], 0, s[36:37]
	s_add_i32 m0, s55, 0x1a000
	s_add_i32 s65, s55, 0x8000
	s_add_i32 s66, s55, 0xa000
	v_bitop3_b32 v246, v16, s24, v13 bitop3:0xde
	global_load_lds_dwordx4 v[4:5], off
	v_lshl_add_u64 v[0:1], v[0:1], 0, s[36:37]
	s_mov_b32 m0, s65
	s_add_u32 s24, s50, 0x40080
	global_load_lds_dwordx4 v[0:1], off
	v_lshl_add_u64 v[0:1], v[2:3], 0, s[36:37]
	s_mov_b32 m0, s66
	s_addc_u32 s25, s51, 0
	global_load_lds_dwordx4 v[0:1], off
	s_add_i32 m0, s55, 0x1c000
	v_lshl_add_u64 v[0:1], s[24:25], 0, v[198:199]
	global_load_lds_dwordx4 v[0:1], off
	v_lshl_add_u64 v[0:1], s[24:25], 0, v[194:195]
	s_add_i32 m0, s55, 0x1e000
	s_cmpk_lt_u32 s45, 0x100
	global_load_lds_dwordx4 v[0:1], off
	v_lshl_or_b32 v247, s26, 5, v17
	s_cselect_b64 s[24:25], -1, 0
	s_and_b32 s27, s45, 0xfffff00
	s_lshl_b32 s26, s26, 6
	s_or_b32 s26, s26, s27
	s_add_u32 s67, s41, 0xeb00000
	s_addc_u32 s68, s44, 0
	v_or3_b32 v0, s26, v192, v15
	s_add_u32 s26, s41, 0x1b700000
	s_addc_u32 s27, s44, 0
	s_add_u32 s69, s19, 0xe00000
	s_addc_u32 s70, s40, 0
	s_add_u32 s28, s19, 0x1000000
	s_addc_u32 s29, s40, 0
	v_lshlrev_b32_e32 v248, 4, v0
	s_add_u32 s71, s43, 0xd700000
	v_lshlrev_b32_e32 v0, 14, v12
	s_addc_u32 s72, s49, 0
	s_ashr_i32 s19, s30, 5
	v_and_b32_e32 v0, 0xffff8000, v0
	s_mul_hi_i32 s31, s19, 0x1c00000
	s_mul_i32 s19, s19, 0x1c00000
	v_lshl_add_u32 v0, v11, 11, v0
	v_and_b32_e32 v1, 1, v12
	s_add_u32 s19, s71, s19
	v_lshl_or_b32 v0, v1, 6, v0
	s_addc_u32 s31, s72, s31
	s_lshl_b32 s30, s30, 17
	v_lshl_add_u32 v204, v14, 1, v0
	v_lshlrev_b32_e32 v0, 14, v8
	s_and_b32 s30, s30, 0x3e0000
	v_and_b32_e32 v0, 0xffff8000, v0
	s_add_u32 s19, s19, s30
	v_lshl_add_u32 v0, v9, 11, v0
	v_and_b32_e32 v1, 1, v8
	s_waitcnt vmcnt(6)
	s_addc_u32 s31, s31, 0
	v_lshl_or_b32 v0, v1, 6, v0
	s_add_u32 s30, s19, 0x800000
	v_lshl_add_u32 v206, v10, 1, v0
	v_mov_b32_e32 v0, 0
	v_lshl_or_b32 v245, s47, 6, v15
	s_addc_u32 s31, s31, 0
	v_lshl_add_u64 v[202:203], s[10:11], 0, v[192:193]
	v_mov_b32_e32 v205, v193
	v_mov_b32_e32 v207, v193
	s_mov_b32 s43, 0
	v_add_u32_e32 v249, 0, v18
	s_mov_b32 s73, 0
	v_mov_b64_e32 v[0:1], 0
	v_mov_b64_e32 v[2:3], 0
	v_mov_b64_e32 v[4:5], 0
	v_mov_b64_e32 v[6:7], 0
	v_mov_b64_e32 v[8:9], 0
	v_mov_b64_e32 v[10:11], 0
	v_mov_b64_e32 v[12:13], 0
	v_mov_b64_e32 v[14:15], 0
	v_mov_b64_e32 v[16:17], 0
	v_mov_b64_e32 v[18:19], 0
	v_mov_b64_e32 v[20:21], 0
	v_mov_b64_e32 v[22:23], 0
	v_mov_b64_e32 v[24:25], 0
	v_mov_b64_e32 v[26:27], 0
	v_mov_b64_e32 v[28:29], 0
	v_mov_b64_e32 v[30:31], 0
	v_mov_b64_e32 v[32:33], 0
	v_mov_b64_e32 v[34:35], 0
	v_mov_b64_e32 v[36:37], 0
	v_mov_b64_e32 v[38:39], 0
	v_mov_b64_e32 v[40:41], 0
	v_mov_b64_e32 v[42:43], 0
	v_mov_b64_e32 v[44:45], 0
	v_mov_b64_e32 v[46:47], 0
	v_mov_b64_e32 v[48:49], 0
	v_mov_b64_e32 v[50:51], 0
	v_mov_b64_e32 v[52:53], 0
	v_mov_b64_e32 v[54:55], 0
	v_mov_b64_e32 v[56:57], 0
	v_mov_b64_e32 v[58:59], 0
	v_mov_b64_e32 v[60:61], 0
	v_mov_b64_e32 v[62:63], 0
	v_mov_b64_e32 v[64:65], 0
	v_mov_b64_e32 v[66:67], 0
	v_mov_b64_e32 v[68:69], 0
	v_mov_b64_e32 v[70:71], 0
	v_mov_b64_e32 v[72:73], 0
	v_mov_b64_e32 v[74:75], 0
	v_mov_b64_e32 v[76:77], 0
	v_mov_b64_e32 v[78:79], 0
	v_mov_b64_e32 v[80:81], 0
	v_mov_b64_e32 v[82:83], 0
	v_mov_b64_e32 v[84:85], 0
	v_mov_b64_e32 v[86:87], 0
	v_mov_b64_e32 v[88:89], 0
	v_mov_b64_e32 v[90:91], 0
	v_mov_b64_e32 v[92:93], 0
	v_mov_b64_e32 v[94:95], 0
	v_mov_b64_e32 v[96:97], 0
	v_mov_b64_e32 v[98:99], 0
	v_mov_b64_e32 v[100:101], 0
	v_mov_b64_e32 v[102:103], 0
	v_mov_b64_e32 v[104:105], 0
	v_mov_b64_e32 v[106:107], 0
	v_mov_b64_e32 v[108:109], 0
	v_mov_b64_e32 v[110:111], 0
	v_mov_b64_e32 v[112:113], 0
	v_mov_b64_e32 v[114:115], 0
	v_mov_b64_e32 v[116:117], 0
	v_mov_b64_e32 v[118:119], 0
	v_mov_b64_e32 v[120:121], 0
	v_mov_b64_e32 v[122:123], 0
	v_mov_b64_e32 v[124:125], 0
	v_mov_b64_e32 v[126:127], 0
	s_mov_b64 s[44:45], s[34:35]
	s_mov_b32 s4, 0x10000
	s_mov_b32 s5, 0x12000
	s_mov_b32 s6, 0x14000
	s_mov_b32 s7, 0x16000
	s_mov_b32 s79, 0x18000
	s_mov_b32 s85, 0x1a000
	s_mov_b32 s87, 0x1c000
	s_barrier
	s_branch .LBB0_471

; template <class Epi, class Sched, bool ALIGN_EPI = false, bool SP2 = false>
; __device__ __forceinline__ void gemm_phase(PG8_LAS unsigned char* lds, const Gemm g, const Sched& S, const Epi& E) {
;     ...
;         if (!has_next) break;
;         if (epi_now) {
; #pragma unroll
;         for (int a = 0; a < 2; ++a)
; #pragma unroll
;             for (int b = 0; b < 2; ++b)
; #pragma unroll
;                 for (int m = 0; m < 4; ++m)
; #pragma unroll
;                     for (int n = 0; n < 2; ++n) acc[a][b][m][n] = (f32x4){0.f, 0.f, 0.f, 0.f};
;         }
;         cur = nxt; cA = nA; cB = nB; ++ui;
.LBB0_560:
	s_and_b64 vcc, exec, s[40:41]
	s_mov_b64 s[40:41], -1
	s_cbranch_vccnz .LBB0_470
	s_andn2_b64 vcc, exec, s[34:35]
	s_cbranch_vccnz .LBB0_563
	v_mov_b32_e32 v0, 0
	v_mov_b64_e32 v[0:1], 0
	v_mov_b64_e32 v[2:3], 0
	v_mov_b64_e32 v[4:5], 0
	v_mov_b64_e32 v[6:7], 0
	v_mov_b64_e32 v[8:9], 0
	v_mov_b64_e32 v[10:11], 0
	v_mov_b64_e32 v[12:13], 0
	v_mov_b64_e32 v[14:15], 0
	v_mov_b64_e32 v[16:17], 0
	v_mov_b64_e32 v[18:19], 0
	v_mov_b64_e32 v[20:21], 0
	v_mov_b64_e32 v[22:23], 0
	v_mov_b64_e32 v[24:25], 0
	v_mov_b64_e32 v[26:27], 0
	v_mov_b64_e32 v[28:29], 0
	v_mov_b64_e32 v[30:31], 0
	v_mov_b64_e32 v[32:33], 0
	v_mov_b64_e32 v[34:35], 0
	v_mov_b64_e32 v[36:37], 0
	v_mov_b64_e32 v[38:39], 0
	v_mov_b64_e32 v[40:41], 0
	v_mov_b64_e32 v[42:43], 0
	v_mov_b64_e32 v[44:45], 0
	v_mov_b64_e32 v[46:47], 0
	v_mov_b64_e32 v[48:49], 0
	v_mov_b64_e32 v[50:51], 0
	v_mov_b64_e32 v[52:53], 0
	v_mov_b64_e32 v[54:55], 0
	v_mov_b64_e32 v[56:57], 0
	v_mov_b64_e32 v[58:59], 0
	v_mov_b64_e32 v[60:61], 0
	v_mov_b64_e32 v[62:63], 0
	v_mov_b64_e32 v[64:65], 0
	v_mov_b64_e32 v[66:67], 0
	v_mov_b64_e32 v[68:69], 0
	v_mov_b64_e32 v[70:71], 0
	v_mov_b64_e32 v[72:73], 0
	v_mov_b64_e32 v[74:75], 0
	v_mov_b64_e32 v[76:77], 0
	v_mov_b64_e32 v[78:79], 0
	v_mov_b64_e32 v[80:81], 0
	v_mov_b64_e32 v[82:83], 0
	v_mov_b64_e32 v[84:85], 0
	v_mov_b64_e32 v[86:87], 0
	v_mov_b64_e32 v[88:89], 0
	v_mov_b64_e32 v[90:91], 0
	v_mov_b64_e32 v[92:93], 0
	v_mov_b64_e32 v[94:95], 0
	v_mov_b64_e32 v[96:97], 0
	v_mov_b64_e32 v[98:99], 0
	v_mov_b64_e32 v[100:101], 0
	v_mov_b64_e32 v[102:103], 0
	v_mov_b64_e32 v[104:105], 0
	v_mov_b64_e32 v[106:107], 0
	v_mov_b64_e32 v[108:109], 0
	v_mov_b64_e32 v[110:111], 0
	v_mov_b64_e32 v[112:113], 0
	v_mov_b64_e32 v[114:115], 0
	v_mov_b64_e32 v[116:117], 0
	v_mov_b64_e32 v[118:119], 0
	v_mov_b64_e32 v[120:121], 0
	v_mov_b64_e32 v[122:123], 0
	v_mov_b64_e32 v[124:125], 0
	v_mov_b64_e32 v[126:127], 0

;     __device__ __forceinline__ const char* aptr(const Unit& u, const Gemm& g) const { return (const char*)g.A + (long)(u.pm >> 4) * g.adj; }
;     __device__ __forceinline__ const char* bptr(const Unit&, const Gemm& g) const { return (const char*)g.Bt; }
;     __device__ __forceinline__ bool next(int i, Unit& u) const { const int r = i / 9, tile = t0 + r * ts; if (r >= nr || tile >= 512) return false; u.pm = tile >> 2; u.pn = tile & 3; u.kind = i % 9; return true; }
; template <class Epi, class Sched, bool ALIGN_EPI = false, bool SP2 = false>
; __device__ __forceinline__ void gemm_phase(PG8_LAS unsigned char* lds, const Gemm g, const Sched& S, const Epi& E) {
;     ...
;         const bool has_next = S.next(ui + 1, nxt);
;         const char* nA = has_next ? S.aptr(nxt, g) + (size_t)nxt.pm * tstep : cA; const char* nB = has_next ? S.bptr(nxt, g) + (size_t)nxt.pn * tstep : cB;
;     ...
;         if (epi_now) {
; #pragma unroll
;         for (int a = 0; a < 2; ++a)
; #pragma unroll
;             for (int b = 0; b < 2; ++b)
; #pragma unroll
;                 for (int m = 0; m < 4; ++m)
; #pragma unroll
;                     for (int n = 0; n < 2; ++n) acc[a][b][m][n] = (f32x4){0.f, 0.f, 0.f, 0.f};
;         }
;         cur = nxt; cA = nA; cB = nB; ++ui;
.LBB0_576:
	s_ashr_i32 s29, s28, 31
	s_lshl_b64 s[10:11], s[28:29], 19
	s_add_u32 s30, s3, s10
	s_addc_u32 s31, s8, s11
	s_and_b64 s[10:11], s[40:41], exec
	s_cselect_b32 s29, s31, s45
	s_cselect_b32 s43, s30, s44
	s_ashr_i32 s27, s26, 31
	s_lshl_b64 s[10:11], s[26:27], 19
	s_add_u32 s34, s14, s10
	s_addc_u32 s35, s18, s11
	s_and_b64 s[10:11], s[40:41], exec
	s_cselect_b32 s27, s35, s47
	s_cselect_b32 s60, s34, s46
	s_add_u32 s44, s44, 0x40080
	s_addc_u32 s45, s45, 0
	s_add_u32 s61, s46, 0x100
	v_mov_b32_e32 v0, 0
	s_addc_u32 s62, s47, 0
	s_mov_b32 s63, -2
	v_mov_b64_e32 v[0:1], 0
	v_mov_b64_e32 v[2:3], 0
	v_mov_b64_e32 v[8:9], 0
	v_mov_b64_e32 v[10:11], 0
	v_mov_b64_e32 v[16:17], 0
	v_mov_b64_e32 v[18:19], 0
	v_mov_b64_e32 v[24:25], 0
	v_mov_b64_e32 v[26:27], 0
	v_mov_b64_e32 v[32:33], 0
	v_mov_b64_e32 v[34:35], 0
	v_mov_b64_e32 v[40:41], 0
	v_mov_b64_e32 v[42:43], 0
	v_mov_b64_e32 v[48:49], 0
	v_mov_b64_e32 v[50:51], 0
	v_mov_b64_e32 v[56:57], 0
	v_mov_b64_e32 v[58:59], 0
	v_mov_b64_e32 v[4:5], 0
	v_mov_b64_e32 v[6:7], 0
	v_mov_b64_e32 v[12:13], 0
	v_mov_b64_e32 v[14:15], 0
	v_mov_b64_e32 v[20:21], 0
	v_mov_b64_e32 v[22:23], 0
	v_mov_b64_e32 v[28:29], 0
	v_mov_b64_e32 v[30:31], 0
	v_mov_b64_e32 v[36:37], 0
	v_mov_b64_e32 v[38:39], 0
	v_mov_b64_e32 v[44:45], 0
	v_mov_b64_e32 v[46:47], 0
	v_mov_b64_e32 v[52:53], 0
	v_mov_b64_e32 v[54:55], 0
	v_mov_b64_e32 v[60:61], 0
	v_mov_b64_e32 v[62:63], 0
	v_mov_b64_e32 v[64:65], 0
	v_mov_b64_e32 v[66:67], 0
	v_mov_b64_e32 v[72:73], 0
	v_mov_b64_e32 v[74:75], 0
	v_mov_b64_e32 v[80:81], 0
	v_mov_b64_e32 v[82:83], 0
	v_mov_b64_e32 v[88:89], 0
	v_mov_b64_e32 v[90:91], 0
	v_mov_b64_e32 v[96:97], 0
	v_mov_b64_e32 v[98:99], 0
	v_mov_b64_e32 v[104:105], 0
	v_mov_b64_e32 v[106:107], 0
	v_mov_b64_e32 v[112:113], 0
	v_mov_b64_e32 v[114:115], 0
	v_mov_b64_e32 v[120:121], 0
	v_mov_b64_e32 v[122:123], 0
	v_mov_b64_e32 v[68:69], 0
	v_mov_b64_e32 v[70:71], 0
	v_mov_b64_e32 v[76:77], 0
	v_mov_b64_e32 v[78:79], 0
	v_mov_b64_e32 v[84:85], 0
	v_mov_b64_e32 v[86:87], 0
	v_mov_b64_e32 v[92:93], 0
	v_mov_b64_e32 v[94:95], 0
	v_mov_b64_e32 v[100:101], 0
	v_mov_b64_e32 v[102:103], 0
	v_mov_b64_e32 v[108:109], 0
	v_mov_b64_e32 v[110:111], 0
	v_mov_b64_e32 v[116:117], 0
	v_mov_b64_e32 v[118:119], 0
	v_mov_b64_e32 v[124:125], 0
	v_mov_b64_e32 v[126:127], 0
